# v54 + grid barrier poll loops without s_sleep
# baseline (speedup 1.0000x reference)
; __global__ void __launch_bounds__(512, 2) mega(Params p) {
;     ...
;     if (ph + 1 < p.ph_hi) {
;       if (ph == p.ph_lo || (gridDim.x & 7u) != 0u) grid.sync();
;       else grid_bar2((unsigned*)(p.ws + OFF_CTR + 1024), (unsigned)(ph - p.ph_lo), gridDim.x >> 3);
.LBB0_945:
	s_nop 0
	global_load_dword v2, v1, s[2:3] offset:32 sc1
	s_waitcnt vmcnt(0)
	v_and_b32_e32 v2, 0xffff0000, v2
	v_cmp_ne_u32_e32 vcc, v2, v0
	s_or_b64 s[4:5], vcc, s[4:5]
	s_andn2_b64 exec, exec, s[4:5]
	s_cbranch_execnz .LBB0_945

; DI void grid_bar2(unsigned* bar, unsigned epoch, unsigned per_group) {
;     ...
;     while (__hip_atomic_load(bar + (9u + x) * 32, __ATOMIC_RELAXED, __HIP_MEMORY_SCOPE_AGENT) < epoch) __builtin_amdgcn_s_sleep(1);
;     __threadfence();
;     asm volatile("s_waitcnt vmcnt(0)" ::: "memory");
;   }
;   __syncthreads();
; __global__ void __launch_bounds__(512, 2) mega(Params p) {
;     ...
;   for (int ph = p.ph_lo; ph < p.ph_hi; ++ph) {
.LBB0_958:
	s_nop 0
	global_load_dword v0, v1, s[2:3] offset:1152 sc1
	s_waitcnt vmcnt(0)
	v_cmp_gt_u32_e32 vcc, s9, v0
	s_cbranch_vccnz .LBB0_958
	s_branch .LBB0_2
